# v11 + only the P5 (gate_up) GEMM stages operand tiles row-major with XOR chunk swizzle (whole-line LDS-DMA)
# baseline (speedup 1.0000x reference)
; #define PG8_STAGE(bufoff, gbase, voff) do { _Pragma("unroll") for (int _i = 0; _i < 2; ++_i) \
;         __builtin_amdgcn_global_load_lds((const unsigned*)((const char*)(gbase) + (voff)[_i]), (PG8_LAS unsigned*)(lds + (bufoff) + ldsw + _i * 8192), 16, 0, 0); } while (0)
; #define PG8_WAIT_V(n) asm volatile("s_waitcnt vmcnt(" #n ")" ::: "memory")
; #define PG8_BAR __builtin_amdgcn_s_barrier()
; template <class Epi, class Sched, bool ALIGN_EPI = false, bool SP2 = false>
; __device__ __forceinline__ void gemm_phase(PG8_LAS unsigned char* lds, const Gemm g, const Sched& S, const Epi& E) {
;     const int tid = threadIdx.x, wid = __builtin_amdgcn_readfirstlane(tid >> 6), lane = tid & 63, wr = wid >> 2, wc = wid & 3, fr = lane & 15, fq = lane >> 4;
;     const int K = g.K, nt = K / BK;
;     unsigned voffA[2], voffB[2];
; #pragma unroll
;     for (int i = 0; i < 2; ++i) { int R, C; stage_rc(tid * 16 + i * 8192, R, C); const int Rb = Epi::PERM ? ((R & ~31) + perm32(R & 31)) : R;
;         voffA[i] = (unsigned)(R * K + C) * 2u; voffB[i] = (unsigned)(Rb * K + C) * 2u; }
;     const size_t kstep = (size_t)(BK * 2);
;     const size_t hstep = (size_t)HALF * K * 2;
;     const size_t tstep = 2 * hstep;
;     const unsigned ldsw = (unsigned)wid * 1024u;
;     const int aoff = lds_byte(wr * 64 + fr, fq * 8), boff = lds_byte(wc * 32 + fr, fq * 8);
;     ...
;     if constexpr (SP2) {
;         PG8_STAGE(PG8_SB(0, 0), cB, voffB); PG8_STAGE(PG8_SB(0, 1), cB + hstep, voffB); PG8_STAGE(PG8_SA(0, 0), cA, voffA); PG8_STAGE(PG8_SA(0, 1), cA + hstep, voffA);
;         if (wr == 1) PG8_BAR;
;         PG8_WAIT_V(2); PG8_BAR;
;         PG8_STAGE(PG8_SB(1, 0), cB + kstep, voffB); PG8_STAGE(PG8_SA(1, 0), cA + kstep, voffA); PG8_STAGE(PG8_SB(1, 1), cB + hstep + kstep, voffB);
;         PG8_WAIT_V(6); PG8_BAR;
.LBB0_761:
	s_cmp_lt_i32 s28, 6
	s_cselect_b64 s[0:1], -1, 0
	s_and_b64 s[0:1], s[0:1], s[4:5]
	s_andn2_b64 vcc, exec, s[0:1]
	s_cbranch_vccnz .LBB0_778
	s_cmpk_gt_i32 s2, 0xaff
	v_readfirstlane_b32 s3, v164
	s_cbranch_scc1 .LBB0_778
	v_and_b32_e32 v240, 7, v164
	v_bfe_u32 v241, v164, 4, 3
	v_xor_b32_e32 v240, v240, v241
	v_lshlrev_b32_e32 v240, 4, v240
	v_lshrrev_b32_e32 v241, 3, v164
	v_lshl_or_b32 v242, v241, 11, v240
	v_add_u32_e32 v243, 0x20000, v242
	v_bfe_u32 v244, v164, 5, 2
	v_lshlrev_b32_e32 v244, 3, v244
	v_bfe_u32 v245, v164, 7, 1
	v_lshl_or_b32 v244, v245, 2, v244
	v_bfe_u32 v245, v164, 3, 2
	v_or_b32_e32 v244, v244, v245
	v_bfe_u32 v245, v164, 8, 1
	v_lshl_or_b32 v244, v245, 5, v244
	v_lshl_or_b32 v244, v244, 11, v240
	v_add_u32_e32 v245, 0x20000, v244
	v_and_b32_e32 v246, 15, v164
	v_bfe_u32 v247, v164, 4, 2
	v_bfe_u32 v248, v164, 1, 3
	v_xor_b32_e32 v247, v247, v248
	v_lshlrev_b32_e32 v247, 4, v247
	v_lshl_or_b32 v246, v246, 7, v247
	v_lshrrev_b32_e32 v0, 5, v164
	v_lshrrev_b32_e32 v2, 1, v164
	v_and_b32_e32 v0, 4, v0
	v_bfe_u32 v1, v164, 2, 2
	v_and_b32_e32 v2, 24, v2
	v_or3_b32 v0, v0, v1, v2
	v_lshlrev_b32_e32 v1, 4, v164
	v_add_u32_e32 v8, 0x2000, v1
	v_lshrrev_b32_e32 v2, 7, v8
	s_movk_i32 s4, 0xe0
	v_and_b32_e32 v4, 32, v164
	s_waitcnt lgkmcnt(0)
	v_and_or_b32 v3, v2, s4, v0
	v_bitop3_b32 v9, v1, v4, 48 bitop3:0x6c
	v_and_b32_e32 v10, 64, v164
	v_bfe_u32 v11, v164, 2, 4
	s_movk_i32 s4, 0xf0
	v_or_b32_e32 v1, v9, v10
	v_and_or_b32 v2, v2, s4, v11
	v_mov_b32_e32 v130, v243
	v_lshrrev_b32_e32 v2, 3, v164
	s_movk_i32 s4, 0x60
	v_and_or_b32 v0, v2, s4, v0
	s_movk_i32 s4, 0x70
	v_mov_b32_e32 v132, v244
	v_and_or_b32 v0, v2, s4, v11
	s_mul_hi_i32 s4, s2, 0x2e8ba2e9
	s_lshr_b32 s7, s4, 31
	s_ashr_i32 s4, s4, 9
	s_add_i32 s4, s4, s7
	s_mulk_i32 s4, 0xb00
	s_sub_i32 s4, s2, s4
	s_sext_i32_i16 s7, s4
	s_bfe_u32 s7, s7, 0x3001c
	s_add_i32 s7, s4, s7
	s_sext_i32_i16 s8, s7
	s_and_b32 s7, s7, 0xfff8
	s_lshr_b32 s5, s3, 6
	s_sub_i32 s4, s4, s7
	s_lshr_b32 s16, s3, 8
	s_lshl_b32 s6, s5, 10
	s_ashr_i32 s8, s8, 3
	s_sext_i32_i16 s7, s4
	s_cmp_lt_i32 s7, 0
	s_movk_i32 s7, 0x161
	s_cselect_b32 s9, s7, 0x160
	s_mul_i32 s4, s4, s9
	s_add_i32 s4, s4, s8
	s_sext_i32_i16 s8, s4
	s_mulk_i32 s8, 0xba3
	s_lshr_b32 s9, s8, 31
	s_ashr_i32 s8, s8, 19
	s_add_i32 s8, s8, s9
	s_lshl_b32 s9, s8, 3
	s_mulk_i32 s8, 0xb0
	s_sub_i32 s8, s4, s8
	s_sext_i32_i16 s4, s8
	s_bfe_u32 s4, s4, 0x3001c
	s_add_i32 s14, s8, s4
	s_sext_i32_i16 s4, s14
	s_and_b32 s14, s14, 0xfff8
	s_sub_i32 s8, s8, s14
	s_sext_i32_i16 s8, s8
	s_lshr_b32 s4, s4, 3
	s_add_i32 s36, s9, s8
	s_ashr_i32 s37, s36, 31
	s_bfe_i64 s[8:9], s[4:5], 0x100000
	s_lshl_b64 s[14:15], s[36:37], 19
	s_lshl_b64 s[8:9], s[8:9], 19
	s_add_u32 s40, s60, s8
	s_addc_u32 s41, s61, s9
	s_add_i32 s8, s6, 0
	s_add_i32 m0, s8, 0x10000
	v_mov_b32_e32 v128, v245
	global_load_lds_dwordx4 v132, s[40:41]
	s_add_i32 m0, s8, 0x12000
	s_add_u32 s18, s40, 0x40000
	global_load_lds_dwordx4 v128, s[40:41]
	s_addc_u32 s19, s41, 0
	s_add_i32 m0, s8, 0x14000
	v_mov_b32_e32 v134, v242
	global_load_lds_dwordx4 v132, s[18:19]
	s_add_i32 m0, s8, 0x16000
	s_add_u32 s38, s10, s14
	s_addc_u32 s39, s11, s15
	s_add_i32 s9, s8, 0x2000
	global_load_lds_dwordx4 v128, s[18:19]
	s_mov_b32 m0, s8
	s_add_u32 s14, s38, 0x40000
	global_load_lds_dwordx4 v134, s[38:39]
	s_mov_b32 m0, s9
	s_addc_u32 s15, s39, 0
	s_add_i32 s34, s8, 0x4000
	global_load_lds_dwordx4 v130, s[38:39]
	s_mov_b32 m0, s34
	s_add_i32 s35, s8, 0x6000
	global_load_lds_dwordx4 v134, s[14:15]
	s_mov_b32 m0, s35
	v_mov_b32_e32 v133, 0
	global_load_lds_dwordx4 v130, s[14:15]
	v_mov_b32_e32 v129, v133
	v_mov_b32_e32 v135, v133
	v_mov_b32_e32 v131, v133
	s_cmp_eq_u32 s16, 1
	s_mov_b64 s[64:65], s[48:49]
	s_mov_b32 s37, 0
	v_lshl_add_u64 v[6:7], s[40:41], 0, v[132:133]
	v_lshl_add_u64 v[4:5], s[40:41], 0, v[128:129]
	v_lshl_add_u64 v[0:1], s[38:39], 0, v[134:135]
	s_cselect_b64 s[14:15], -1, 0
	s_cmp_lg_u32 s16, 1
	v_lshl_add_u64 v[2:3], s[38:39], 0, v[130:131]
	s_cbranch_scc1 .LBB0_765
	s_barrier
.LBB0_765:
	s_lshl_b32 s44, s16, 6
	s_lshl_b32 s20, s16, 13
	s_lshl_b32 s5, s5, 5
	s_mov_b64 s[16:17], 0x80
	s_and_b32 s5, s5, 0x60
	s_add_i32 m0, s8, 0x18000
	v_lshl_add_u64 v[6:7], v[6:7], 0, s[16:17]
	s_lshl_b32 s21, s5, 7
	s_ashr_i32 s45, s2, 31
	s_waitcnt vmcnt(2)
	s_barrier
	global_load_lds_dwordx4 v[6:7], off
	v_lshl_add_u64 v[4:5], v[4:5], 0, s[16:17]
	s_add_i32 m0, s8, 0x1a000
	s_add_i32 s46, s8, 0x8000
	s_add_i32 s47, s8, 0xa000
	global_load_lds_dwordx4 v[4:5], off
	v_lshl_add_u64 v[0:1], v[0:1], 0, s[16:17]
	s_mov_b32 m0, s46
	s_add_u32 s18, s40, 0x40080
	global_load_lds_dwordx4 v[0:1], off
	v_lshl_add_u64 v[0:1], v[2:3], 0, s[16:17]
	s_mov_b32 m0, s47
	s_addc_u32 s19, s41, 0
	global_load_lds_dwordx4 v[0:1], off
	s_add_i32 m0, s8, 0x1c000
	v_lshl_add_u64 v[0:1], s[18:19], 0, v[132:133]
	global_load_lds_dwordx4 v[0:1], off
	v_lshl_add_u64 v[0:1], s[18:19], 0, v[128:129]
	s_add_i32 m0, s8, 0x1e000
	s_sext_i32_i16 s52, s4
	global_load_lds_dwordx4 v[0:1], off
	v_bfe_u32 v0, v164, 4, 2
	v_and_b32_e32 v148, 15, v164
	v_lshlrev_b32_e32 v1, 4, v0
	v_lshlrev_b32_e32 v3, 2, v164
	v_lshlrev_b32_e32 v4, 6, v164
	s_movk_i32 s4, 0x3c0
	v_lshl_or_b32 v2, v148, 6, v1
	v_and_b32_e32 v3, 32, v3
	v_and_or_b32 v1, v4, s4, v1
	v_lshl_or_b32 v150, v0, 3, s5
	v_lshlrev_b32_e32 v0, 8, v164
	v_or_b32_e32 v149, s21, v246
	v_and_b32_e32 v0, 0x38000, v0
	v_lshlrev_b32_e32 v1, 11, v11
	v_or3_b32 v0, v9, v0, v1
	v_mov_b32_e32 v136, v242
	v_lshlrev_b32_e32 v0, 4, v8
	v_and_b32_e32 v0, 0x78000, v0
	v_or3_b32 v0, v9, v0, v1
	v_mov_b32_e32 v138, v243
	v_mbcnt_lo_u32_b32 v0, -1, 0
	s_waitcnt vmcnt(6)
	s_cmpk_lt_u32 s3, 0x100
	v_mbcnt_hi_u32_b32 v0, -1, v0
	v_or_b32_e32 v2, s20, v246
	s_cselect_b64 s[18:19], -1, 0
	s_add_i32 s49, 0, 0x10000
	s_add_i32 s50, 0, 0x14000
	v_and_or_b32 v0, v0, 64, v148
	s_ashr_i32 s48, s33, 31
	v_mov_b32_e32 v137, v133
	v_mov_b32_e32 v139, v133
	v_mov_b64_e32 v[140:141], 0xb00
	v_mov_b64_e32 v[142:143], 0xaff
	v_add_u32_e32 v151, s49, v149
	v_xor_b32_e32 v249, 64, v151
	v_add_u32_e32 v152, s50, v149
	v_xor_b32_e32 v250, 64, v152
	v_add_u32_e32 v153, 0, v2
	v_xor_b32_e32 v251, 64, v153
	v_mov_b32_e32 v154, 0x358637bd
	v_lshlrev_b32_e32 v155, 2, v0
	s_movk_i32 s51, 0x1600
	s_barrier
	s_branch .LBB0_768

; #define PG8_STAGE(bufoff, gbase, voff) do { _Pragma("unroll") for (int _i = 0; _i < 2; ++_i) \
;         __builtin_amdgcn_global_load_lds((const unsigned*)((const char*)(gbase) + (voff)[_i]), (PG8_LAS unsigned*)(lds + (bufoff) + ldsw + _i * 8192), 16, 0, 0); } while (0)
; #define PG8_LDA(dst, b, h) do { _Pragma("unroll") for (int m = 0; m < 4; ++m) _Pragma("unroll") for (int k = 0; k < 2; ++k) dst[m][k] = *(const PG8_LAS bf16x8*)(lds + PG8_SA(b, h) + aoff + m * 2048 + k * 1024); } while (0)
; #define PG8_LDB(dst, b, h) do { _Pragma("unroll") for (int n = 0; n < 2; ++n) _Pragma("unroll") for (int k = 0; k < 2; ++k) dst[n][k] = *(const PG8_LAS bf16x8*)(lds + PG8_SB(b, h) + boff + n * 2048 + k * 1024); } while (0)
; #define PG8_MMA(ai, bj, At, Bt) do { __builtin_amdgcn_s_setprio(1); _Pragma("unroll") for (int m = 0; m < 4; ++m) _Pragma("unroll") for (int n = 0; n < 2; ++n) _Pragma("unroll") for (int k = 0; k < 2; ++k) \
;         acc[ai][bj][m][n] = __builtin_amdgcn_mfma_f32_16x16x32_bf16(Bt[n][k], At[m][k], acc[ai][bj][m][n], 0, 0, 0); __builtin_amdgcn_s_setprio(0); } while (0)
; #define PG8_WAIT_V(n) asm volatile("s_waitcnt vmcnt(" #n ")" ::: "memory")
; #define PG8_WAIT_L(n) asm volatile("s_waitcnt lgkmcnt(" #n ")" ::: "memory")
; #define PG8_BAR __builtin_amdgcn_s_barrier()
; #define PG8_SCHED __builtin_amdgcn_sched_barrier(0)
; template <class Epi, class Sched, bool ALIGN_EPI = false, bool SP2 = false>
; __device__ __forceinline__ void gemm_phase(PG8_LAS unsigned char* lds, const Gemm g, const Sched& S, const Epi& E) {
;     ...
;             PG8_LDB(B0, 0, 0); PG8_LDB(B1, 0, 1); PG8_SCHED; PG8_LDA(At, 0, 0); PG8_STAGE(PG8_SA(1, 1), a1 + hstep, voffA);
;             PG8_WAIT_V(8); PG8_WAIT_L(0); PG8_BAR; PG8_MMA(0, 0, At, B0); PG8_MMA(0, 1, At, B1); PG8_BAR; PG8_SCHED;
;             PG8_LDA(At, 0, 1); PG8_STAGE(PG8_SB(0, 0), b2, voffB); PG8_STAGE(PG8_SB(0, 1), b2 + hstep, voffB); PG8_STAGE(PG8_SA(0, 0), a2, voffA);
;             PG8_WAIT_V(8); PG8_WAIT_L(0); PG8_BAR; PG8_MMA(1, 0, At, B0); PG8_MMA(1, 1, At, B1); PG8_BAR; PG8_SCHED;
.LBB0_771:
	ds_read_b128 v[144:147], v151
	ds_read_b128 v[156:159], v249
	ds_read_b128 v[160:163], v151 offset:2048
	ds_read_b128 v[166:169], v249 offset:2048
	ds_read_b128 v[170:173], v152
	ds_read_b128 v[174:177], v250
	ds_read_b128 v[178:181], v152 offset:2048
	ds_read_b128 v[182:185], v250 offset:2048
	s_add_u32 s31, s38, 0xfffc0080
	s_addc_u32 s40, s39, -1
	s_cmp_eq_u32 s30, 12
	s_cselect_b32 s43, s21, s40
	s_cselect_b32 s42, s53, s31
	s_cselect_b32 s41, s23, s3
	s_cselect_b32 s40, s54, s55
	s_add_i32 m0, s8, 0xc000
	ds_read_b128 v[186:189], v153
	ds_read_b128 v[190:193], v251
	ds_read_b128 v[194:197], v153 offset:2048
	ds_read_b128 v[198:201], v251 offset:2048
	ds_read_b128 v[202:205], v153 offset:4096
	ds_read_b128 v[206:209], v251 offset:4096
	ds_read_b128 v[210:213], v153 offset:6144
	ds_read_b128 v[214:217], v251 offset:6144
	global_load_lds_dwordx4 v136, s[38:39]
	s_add_i32 m0, s8, 0xe000
	s_nop 0
	global_load_lds_dwordx4 v138, s[38:39]
	s_waitcnt vmcnt(8)
	s_waitcnt lgkmcnt(0)
	s_barrier
	s_setprio 1
	s_waitcnt lgkmcnt(0)
	v_mfma_f32_16x16x32_bf16 v[124:127], v[144:147], v[186:189], v[124:127]
	v_mfma_f32_16x16x32_bf16 v[120:123], v[160:163], v[186:189], v[120:123]
	v_mfma_f32_16x16x32_bf16 v[116:119], v[144:147], v[194:197], v[116:119]
	v_mfma_f32_16x16x32_bf16 v[104:107], v[160:163], v[194:197], v[104:107]
	v_mfma_f32_16x16x32_bf16 v[92:95], v[144:147], v[202:205], v[92:95]
	v_mfma_f32_16x16x32_bf16 v[88:91], v[160:163], v[202:205], v[88:91]
	v_mfma_f32_16x16x32_bf16 v[76:79], v[144:147], v[210:213], v[76:79]
	v_mfma_f32_16x16x32_bf16 v[72:75], v[160:163], v[210:213], v[72:75]
	v_mfma_f32_16x16x32_bf16 v[124:127], v[156:159], v[190:193], v[124:127]
	v_mfma_f32_16x16x32_bf16 v[120:123], v[166:169], v[190:193], v[120:123]
	v_mfma_f32_16x16x32_bf16 v[116:119], v[156:159], v[198:201], v[116:119]
	v_mfma_f32_16x16x32_bf16 v[104:107], v[166:169], v[198:201], v[104:107]
	v_mfma_f32_16x16x32_bf16 v[92:95], v[156:159], v[206:209], v[92:95]
	v_mfma_f32_16x16x32_bf16 v[88:91], v[166:169], v[206:209], v[88:91]
	v_mfma_f32_16x16x32_bf16 v[76:79], v[156:159], v[214:217], v[76:79]
	v_mfma_f32_16x16x32_bf16 v[72:75], v[166:169], v[214:217], v[72:75]
	s_setprio 0
	s_setprio 1
	v_mfma_f32_16x16x32_bf16 v[112:115], v[170:173], v[186:189], v[112:115]
	v_mfma_f32_16x16x32_bf16 v[108:111], v[178:181], v[186:189], v[108:111]
	v_mfma_f32_16x16x32_bf16 v[100:103], v[170:173], v[194:197], v[100:103]
	v_mfma_f32_16x16x32_bf16 v[96:99], v[178:181], v[194:197], v[96:99]
	v_mfma_f32_16x16x32_bf16 v[84:87], v[170:173], v[202:205], v[84:87]
	v_mfma_f32_16x16x32_bf16 v[80:83], v[178:181], v[202:205], v[80:83]
	v_mfma_f32_16x16x32_bf16 v[68:71], v[170:173], v[210:213], v[68:71]
	v_mfma_f32_16x16x32_bf16 v[64:67], v[178:181], v[210:213], v[64:67]
	v_mfma_f32_16x16x32_bf16 v[112:115], v[174:177], v[190:193], v[112:115]
	v_mfma_f32_16x16x32_bf16 v[108:111], v[182:185], v[190:193], v[108:111]
	v_mfma_f32_16x16x32_bf16 v[100:103], v[174:177], v[198:201], v[100:103]
	v_mfma_f32_16x16x32_bf16 v[96:99], v[182:185], v[198:201], v[96:99]
	v_mfma_f32_16x16x32_bf16 v[84:87], v[174:177], v[206:209], v[84:87]
	v_mfma_f32_16x16x32_bf16 v[80:83], v[182:185], v[206:209], v[80:83]
	v_mfma_f32_16x16x32_bf16 v[68:71], v[174:177], v[214:217], v[68:71]
	v_mfma_f32_16x16x32_bf16 v[64:67], v[182:185], v[214:217], v[64:67]
	s_setprio 0
	s_barrier
	s_add_i32 s31, s49, s6
	s_mov_b32 m0, s31
	ds_read_b128 v[186:189], v153 offset:16384
	ds_read_b128 v[190:193], v251 offset:16384
	ds_read_b128 v[194:197], v153 offset:18432
	ds_read_b128 v[198:201], v251 offset:18432
	ds_read_b128 v[202:205], v153 offset:20480
	ds_read_b128 v[206:209], v251 offset:20480
	ds_read_b128 v[210:213], v153 offset:22528
	ds_read_b128 v[214:217], v251 offset:22528
	global_load_lds_dwordx4 v132, s[40:41]
	s_add_i32 m0, s31, 0x2000
	s_add_u32 s58, s40, 0x40000
	s_addc_u32 s59, s41, 0
	s_add_i32 s31, s50, s6
	global_load_lds_dwordx4 v128, s[40:41]
	s_mov_b32 m0, s31
	s_nop 0
	global_load_lds_dwordx4 v132, s[58:59]
	s_add_i32 m0, s31, 0x2000
	s_nop 0
	global_load_lds_dwordx4 v128, s[58:59]
	s_mov_b32 m0, s8
	s_nop 0
	global_load_lds_dwordx4 v134, s[42:43]
	s_mov_b32 m0, s9
	s_nop 0
	global_load_lds_dwordx4 v130, s[42:43]
	s_waitcnt vmcnt(8)
	s_waitcnt lgkmcnt(0)
	s_barrier
	s_setprio 1
	s_waitcnt lgkmcnt(0)
	v_mfma_f32_16x16x32_bf16 v[60:63], v[144:147], v[186:189], v[60:63]
	v_mfma_f32_16x16x32_bf16 v[56:59], v[160:163], v[186:189], v[56:59]
	v_mfma_f32_16x16x32_bf16 v[44:47], v[144:147], v[194:197], v[44:47]
	v_mfma_f32_16x16x32_bf16 v[40:43], v[160:163], v[194:197], v[40:43]
	v_mfma_f32_16x16x32_bf16 v[28:31], v[144:147], v[202:205], v[28:31]
	v_mfma_f32_16x16x32_bf16 v[24:27], v[160:163], v[202:205], v[24:27]
	v_mfma_f32_16x16x32_bf16 v[12:15], v[144:147], v[210:213], v[12:15]
	v_mfma_f32_16x16x32_bf16 v[8:11], v[160:163], v[210:213], v[8:11]
	v_mfma_f32_16x16x32_bf16 v[60:63], v[156:159], v[190:193], v[60:63]
	v_mfma_f32_16x16x32_bf16 v[56:59], v[166:169], v[190:193], v[56:59]
	v_mfma_f32_16x16x32_bf16 v[44:47], v[156:159], v[198:201], v[44:47]
	v_mfma_f32_16x16x32_bf16 v[40:43], v[166:169], v[198:201], v[40:43]
	v_mfma_f32_16x16x32_bf16 v[28:31], v[156:159], v[206:209], v[28:31]
	v_mfma_f32_16x16x32_bf16 v[24:27], v[166:169], v[206:209], v[24:27]
	v_mfma_f32_16x16x32_bf16 v[12:15], v[156:159], v[214:217], v[12:15]
	v_mfma_f32_16x16x32_bf16 v[8:11], v[166:169], v[214:217], v[8:11]
	s_setprio 0
	s_setprio 1
	v_mfma_f32_16x16x32_bf16 v[52:55], v[170:173], v[186:189], v[52:55]
	v_mfma_f32_16x16x32_bf16 v[48:51], v[178:181], v[186:189], v[48:51]
	v_mfma_f32_16x16x32_bf16 v[36:39], v[170:173], v[194:197], v[36:39]
	v_mfma_f32_16x16x32_bf16 v[32:35], v[178:181], v[194:197], v[32:35]
	v_mfma_f32_16x16x32_bf16 v[20:23], v[170:173], v[202:205], v[20:23]
	v_mfma_f32_16x16x32_bf16 v[16:19], v[178:181], v[202:205], v[16:19]
	v_mfma_f32_16x16x32_bf16 v[4:7], v[170:173], v[210:213], v[4:7]
	v_mfma_f32_16x16x32_bf16 v[0:3], v[178:181], v[210:213], v[0:3]
	v_mfma_f32_16x16x32_bf16 v[52:55], v[174:177], v[190:193], v[52:55]
	v_mfma_f32_16x16x32_bf16 v[48:51], v[182:185], v[190:193], v[48:51]
	v_mfma_f32_16x16x32_bf16 v[36:39], v[174:177], v[198:201], v[36:39]
	v_mfma_f32_16x16x32_bf16 v[32:35], v[182:185], v[198:201], v[32:35]
	v_mfma_f32_16x16x32_bf16 v[20:23], v[174:177], v[206:209], v[20:23]
	v_mfma_f32_16x16x32_bf16 v[16:19], v[182:185], v[206:209], v[16:19]
	v_mfma_f32_16x16x32_bf16 v[4:7], v[174:177], v[214:217], v[4:7]
	v_mfma_f32_16x16x32_bf16 v[0:3], v[182:185], v[214:217], v[0:3]
	s_setprio 0
	s_barrier
; #define PG8_STAGE(bufoff, gbase, voff) do { _Pragma("unroll") for (int _i = 0; _i < 2; ++_i) \
;         __builtin_amdgcn_global_load_lds((const unsigned*)((const char*)(gbase) + (voff)[_i]), (PG8_LAS unsigned*)(lds + (bufoff) + ldsw + _i * 8192), 16, 0, 0); } while (0)
; #define PG8_LDA(dst, b, h) do { _Pragma("unroll") for (int m = 0; m < 4; ++m) _Pragma("unroll") for (int k = 0; k < 2; ++k) dst[m][k] = *(const PG8_LAS bf16x8*)(lds + PG8_SA(b, h) + aoff + m * 2048 + k * 1024); } while (0)
; #define PG8_LDB(dst, b, h) do { _Pragma("unroll") for (int n = 0; n < 2; ++n) _Pragma("unroll") for (int k = 0; k < 2; ++k) dst[n][k] = *(const PG8_LAS bf16x8*)(lds + PG8_SB(b, h) + boff + n * 2048 + k * 1024); } while (0)
; #define PG8_MMA(ai, bj, At, Bt) do { __builtin_amdgcn_s_setprio(1); _Pragma("unroll") for (int m = 0; m < 4; ++m) _Pragma("unroll") for (int n = 0; n < 2; ++n) _Pragma("unroll") for (int k = 0; k < 2; ++k) \
;         acc[ai][bj][m][n] = __builtin_amdgcn_mfma_f32_16x16x32_bf16(Bt[n][k], At[m][k], acc[ai][bj][m][n], 0, 0, 0); __builtin_amdgcn_s_setprio(0); } while (0)
; #define PG8_WAIT_V(n) asm volatile("s_waitcnt vmcnt(" #n ")" ::: "memory")
; #define PG8_WAIT_L(n) asm volatile("s_waitcnt lgkmcnt(" #n ")" ::: "memory")
; template <class Epi, class Sched, bool ALIGN_EPI = false, bool SP2 = false>
; __device__ __forceinline__ void gemm_phase(PG8_LAS unsigned char* lds, const Gemm g, const Sched& S, const Epi& E) {
;     ...
;         for (int t = 0; t < nt; t += 2) {
;             const bool last = (t == nt - 2);
;             const char* a1 = cA + (size_t)(t + 1) * kstep;
;             const char* a2 = last ? nA : cA + (size_t)(t + 2) * kstep; const char* b2 = last ? nB : cB + (size_t)(t + 2) * kstep;
;             const char* a3 = a2 + kstep; const char* b3 = b2 + kstep;
;             if (last && has_next) S.a_ready(nxt);
;     ...
;             PG8_LDB(B0, 1, 0); PG8_LDB(B1, 1, 1); PG8_SCHED; PG8_LDA(At, 1, 0); PG8_STAGE(PG8_SA(0, 1), a2 + hstep, voffA);
;             PG8_WAIT_V(8); PG8_WAIT_L(0); PG8_BAR; PG8_MMA(0, 0, At, B0); PG8_MMA(0, 1, At, B1); PG8_BAR; PG8_SCHED;
;             PG8_LDA(At, 1, 1); PG8_STAGE(PG8_SB(1, 0), b3, voffB); PG8_STAGE(PG8_SB(1, 1), b3 + hstep, voffB); PG8_STAGE(PG8_SA(1, 0), a3, voffA);
;             PG8_WAIT_V(8); PG8_WAIT_L(0); PG8_BAR; PG8_MMA(1, 0, At, B0); PG8_MMA(1, 1, At, B1); PG8_BAR; PG8_SCHED;
	s_add_i32 s31, 0, 0x18000
	v_add_u32_e32 v165, s31, v149
	v_xor_b32_e32 v252, 64, v165
	s_add_i32 s58, 0, 0x1c000
	ds_read_b128 v[144:147], v165
	ds_read_b128 v[156:159], v252
	ds_read_b128 v[160:163], v165 offset:2048
	ds_read_b128 v[166:169], v252 offset:2048
	v_add_u32_e32 v165, s58, v149
	v_xor_b32_e32 v252, 64, v165
	ds_read_b128 v[170:173], v165
	ds_read_b128 v[174:177], v252
	ds_read_b128 v[178:181], v165 offset:2048
	ds_read_b128 v[182:185], v252 offset:2048
	s_add_u32 s42, s42, 0x40000
	s_addc_u32 s43, s43, 0
	s_mov_b32 m0, s34
	ds_read_b128 v[186:189], v153 offset:32768
	ds_read_b128 v[190:193], v251 offset:32768
	ds_read_b128 v[194:197], v153 offset:34816
	ds_read_b128 v[198:201], v251 offset:34816
	ds_read_b128 v[202:205], v153 offset:36864
	ds_read_b128 v[206:209], v251 offset:36864
	ds_read_b128 v[210:213], v153 offset:38912
	ds_read_b128 v[214:217], v251 offset:38912
	global_load_lds_dwordx4 v134, s[42:43]
	s_mov_b32 m0, s35
	s_nop 0
	global_load_lds_dwordx4 v130, s[42:43]
	s_waitcnt vmcnt(8)
	s_waitcnt lgkmcnt(0)
	s_barrier
	s_setprio 1
	s_waitcnt lgkmcnt(0)
	v_mfma_f32_16x16x32_bf16 v[124:127], v[144:147], v[186:189], v[124:127]
	v_mfma_f32_16x16x32_bf16 v[120:123], v[160:163], v[186:189], v[120:123]
	v_mfma_f32_16x16x32_bf16 v[116:119], v[144:147], v[194:197], v[116:119]
	v_mfma_f32_16x16x32_bf16 v[104:107], v[160:163], v[194:197], v[104:107]
	v_mfma_f32_16x16x32_bf16 v[92:95], v[144:147], v[202:205], v[92:95]
	v_mfma_f32_16x16x32_bf16 v[88:91], v[160:163], v[202:205], v[88:91]
	v_mfma_f32_16x16x32_bf16 v[76:79], v[144:147], v[210:213], v[76:79]
	v_mfma_f32_16x16x32_bf16 v[72:75], v[160:163], v[210:213], v[72:75]
	v_mfma_f32_16x16x32_bf16 v[124:127], v[156:159], v[190:193], v[124:127]
	v_mfma_f32_16x16x32_bf16 v[120:123], v[166:169], v[190:193], v[120:123]
	v_mfma_f32_16x16x32_bf16 v[116:119], v[156:159], v[198:201], v[116:119]
	v_mfma_f32_16x16x32_bf16 v[104:107], v[166:169], v[198:201], v[104:107]
	v_mfma_f32_16x16x32_bf16 v[92:95], v[156:159], v[206:209], v[92:95]
	v_mfma_f32_16x16x32_bf16 v[88:91], v[166:169], v[206:209], v[88:91]
	v_mfma_f32_16x16x32_bf16 v[76:79], v[156:159], v[214:217], v[76:79]
	v_mfma_f32_16x16x32_bf16 v[72:75], v[166:169], v[214:217], v[72:75]
	s_setprio 0
	s_setprio 1
	v_mfma_f32_16x16x32_bf16 v[112:115], v[170:173], v[186:189], v[112:115]
	v_mfma_f32_16x16x32_bf16 v[108:111], v[178:181], v[186:189], v[108:111]
	v_mfma_f32_16x16x32_bf16 v[100:103], v[170:173], v[194:197], v[100:103]
	v_mfma_f32_16x16x32_bf16 v[96:99], v[178:181], v[194:197], v[96:99]
	v_mfma_f32_16x16x32_bf16 v[84:87], v[170:173], v[202:205], v[84:87]
	v_mfma_f32_16x16x32_bf16 v[80:83], v[178:181], v[202:205], v[80:83]
	v_mfma_f32_16x16x32_bf16 v[68:71], v[170:173], v[210:213], v[68:71]
	v_mfma_f32_16x16x32_bf16 v[64:67], v[178:181], v[210:213], v[64:67]
	v_mfma_f32_16x16x32_bf16 v[112:115], v[174:177], v[190:193], v[112:115]
	v_mfma_f32_16x16x32_bf16 v[108:111], v[182:185], v[190:193], v[108:111]
	v_mfma_f32_16x16x32_bf16 v[100:103], v[174:177], v[198:201], v[100:103]
	v_mfma_f32_16x16x32_bf16 v[96:99], v[182:185], v[198:201], v[96:99]
	v_mfma_f32_16x16x32_bf16 v[84:87], v[174:177], v[206:209], v[84:87]
	v_mfma_f32_16x16x32_bf16 v[80:83], v[182:185], v[206:209], v[80:83]
	v_mfma_f32_16x16x32_bf16 v[68:71], v[174:177], v[214:217], v[68:71]
	v_mfma_f32_16x16x32_bf16 v[64:67], v[182:185], v[214:217], v[64:67]
	s_setprio 0
	s_barrier
	s_add_i32 s31, s31, s6
	s_add_i32 m0, s31, 0xffffff80
	ds_read_b128 v[186:189], v153 offset:49152
	ds_read_b128 v[190:193], v251 offset:49152
	ds_read_b128 v[194:197], v153 offset:51200
	ds_read_b128 v[198:201], v251 offset:51200
	ds_read_b128 v[202:205], v153 offset:53248
	ds_read_b128 v[206:209], v251 offset:53248
	ds_read_b128 v[210:213], v153 offset:55296
	ds_read_b128 v[214:217], v251 offset:55296
	global_load_lds_dwordx4 v132, s[40:41] offset:128
	s_add_i32 m0, s31, 0x1f80
	s_add_i32 s31, s58, s6
	global_load_lds_dwordx4 v128, s[40:41] offset:128
	s_add_u32 s40, s40, 0x40080
	s_addc_u32 s41, s41, 0
	s_mov_b32 m0, s31
	s_nop 0
	global_load_lds_dwordx4 v132, s[40:41]
	s_add_i32 m0, s31, 0x2000
	s_nop 0
	global_load_lds_dwordx4 v128, s[40:41]
	s_sub_u32 s98, s42, 0x3ff80
	s_subb_u32 s99, s43, 0
	s_mov_b32 m0, s46
	s_nop 0
	global_load_lds_dwordx4 v134, s[98:99]
	s_mov_b32 m0, s47
	s_nop 0
	global_load_lds_dwordx4 v130, s[98:99]
	s_waitcnt vmcnt(8)
	s_waitcnt lgkmcnt(0)
	s_barrier
	s_setprio 1
	s_waitcnt lgkmcnt(0)
	v_mfma_f32_16x16x32_bf16 v[60:63], v[144:147], v[186:189], v[60:63]
	v_mfma_f32_16x16x32_bf16 v[56:59], v[160:163], v[186:189], v[56:59]
	v_mfma_f32_16x16x32_bf16 v[44:47], v[144:147], v[194:197], v[44:47]
	v_mfma_f32_16x16x32_bf16 v[40:43], v[160:163], v[194:197], v[40:43]
	v_mfma_f32_16x16x32_bf16 v[28:31], v[144:147], v[202:205], v[28:31]
	v_mfma_f32_16x16x32_bf16 v[24:27], v[160:163], v[202:205], v[24:27]
	v_mfma_f32_16x16x32_bf16 v[12:15], v[144:147], v[210:213], v[12:15]
	v_mfma_f32_16x16x32_bf16 v[8:11], v[160:163], v[210:213], v[8:11]
	v_mfma_f32_16x16x32_bf16 v[60:63], v[156:159], v[190:193], v[60:63]
	v_mfma_f32_16x16x32_bf16 v[56:59], v[166:169], v[190:193], v[56:59]
	v_mfma_f32_16x16x32_bf16 v[44:47], v[156:159], v[198:201], v[44:47]
	v_mfma_f32_16x16x32_bf16 v[40:43], v[166:169], v[198:201], v[40:43]
	v_mfma_f32_16x16x32_bf16 v[28:31], v[156:159], v[206:209], v[28:31]
	v_mfma_f32_16x16x32_bf16 v[24:27], v[166:169], v[206:209], v[24:27]
	v_mfma_f32_16x16x32_bf16 v[12:15], v[156:159], v[214:217], v[12:15]
	v_mfma_f32_16x16x32_bf16 v[8:11], v[166:169], v[214:217], v[8:11]
	s_setprio 0
	s_setprio 1
	v_mfma_f32_16x16x32_bf16 v[52:55], v[170:173], v[186:189], v[52:55]
	v_mfma_f32_16x16x32_bf16 v[48:51], v[178:181], v[186:189], v[48:51]
	v_mfma_f32_16x16x32_bf16 v[36:39], v[170:173], v[194:197], v[36:39]
	v_mfma_f32_16x16x32_bf16 v[32:35], v[178:181], v[194:197], v[32:35]
	v_mfma_f32_16x16x32_bf16 v[20:23], v[170:173], v[202:205], v[20:23]
	v_mfma_f32_16x16x32_bf16 v[16:19], v[178:181], v[202:205], v[16:19]
	v_mfma_f32_16x16x32_bf16 v[4:7], v[170:173], v[210:213], v[4:7]
	v_mfma_f32_16x16x32_bf16 v[0:3], v[178:181], v[210:213], v[0:3]
	v_mfma_f32_16x16x32_bf16 v[52:55], v[174:177], v[190:193], v[52:55]
	v_mfma_f32_16x16x32_bf16 v[48:51], v[182:185], v[190:193], v[48:51]
	v_mfma_f32_16x16x32_bf16 v[36:39], v[174:177], v[198:201], v[36:39]
	v_mfma_f32_16x16x32_bf16 v[32:35], v[182:185], v[198:201], v[32:35]
	v_mfma_f32_16x16x32_bf16 v[20:23], v[174:177], v[206:209], v[20:23]
	v_mfma_f32_16x16x32_bf16 v[16:19], v[182:185], v[206:209], v[16:19]
	v_mfma_f32_16x16x32_bf16 v[4:7], v[174:177], v[214:217], v[4:7]
	v_mfma_f32_16x16x32_bf16 v[0:3], v[182:185], v[214:217], v[0:3]
	s_setprio 0
	s_barrier
	s_add_i32 s30, s30, 2
	s_add_u32 s38, s38, 0x100
	s_addc_u32 s39, s39, 0
	s_add_u32 s55, s55, 0x100
	s_addc_u32 s3, s3, 0
	s_cmp_gt_u32 s30, 13
	s_cbranch_scc0 .LBB0_771
	s_and_b64 vcc, exec, s[18:19]
	s_cbranch_vccz .LBB0_774
	s_barrier
